# v72 + EpiPool (P8 pool GEMM epilogue) hand-written: 16 gate loads and 4 scale vectors in flight
# baseline (speedup 1.0000x reference)
; DI void unpack8(const u32x4 w, float (&f)[8]) { f[0] = bflo(w.x); f[1] = bfhi(w.x); f[2] = bflo(w.y); f[3] = bfhi(w.y); f[4] = bflo(w.z); f[5] = bfhi(w.z); f[6] = bflo(w.w); f[7] = bfhi(w.w); }
; DI u32x4 pack8(const float (&f)[8]) { u32x4 w; w.x = pk2(f[0], f[1]); w.y = pk2(f[2], f[3]); w.z = pk2(f[4], f[5]); w.w = pk2(f[6], f[7]); return w; }
;     DI void operator()(const f32x4 (&acc)[2][2][4][2], const pg8::Unit& u, int wr, int wc, int fr, int fq) const {
;         const int row0 = u.pm * 256 + wr * 64 + fr, colt = u.pn * 256 + wc * 32 + 8 * fq;
; #pragma unroll
;         for (int ai = 0; ai < 2; ++ai)
; #pragma unroll
;             for (int m = 0; m < 4; ++m) { const size_t row = row0 + ai * 128 + m * 16;
; #pragma unroll
;                 for (int bj = 0; bj < 2; ++bj) { const int col = colt + bj * 128; const f32x4 v0 = acc[ai][bj][m][0], v1 = acc[ai][bj][m][1];
;                     float gc[8]; unpack8(__builtin_nontemporal_load((const u32x4*)(Z1 + row * NIN_O + 1024 + col)), gc);
;                     const f32x4 s0 = *(const f32x4*)(ps + col), s1 = *(const f32x4*)(ps + col + 4);
;                     float y[8];
; #pragma unroll
;                     for (int k = 0; k < 4; ++k) { y[k] = v0[k] * s0[k] * gc[k]; y[4 + k] = v1[k] * s1[k] * gc[4 + k]; }
;                     *(u32x4*)(Y + row * 2048 + col) = pack8(y); }
;                 asm volatile("" ::: "memory"); }
;     }
.LBB0_1906:
	v_lshl_or_b32 v142, s87, 8, v151
	v_ashrrev_i32_e32 v143, 31, v142
	v_lshl_add_u32 v146, s48, 8, v149
	v_mov_b64_e32 v[144:145], s[30:31]
	v_lshl_add_u64 v[140:141], v[142:143], 2, s[46:47]
	v_mad_i64_i32 v[244:245], s[54:55], v146, s86, v[144:145]
	v_lshlrev_b64 v[142:143], 1, v[142:143]
	v_lshl_add_u64 v[244:245], v[244:245], 0, v[142:143]
	global_load_dwordx4 v[156:159], v[140:141], off
	global_load_dwordx4 v[160:163], v[140:141], off offset:16
	global_load_dwordx4 v[164:167], v[140:141], off offset:512
	global_load_dwordx4 v[168:171], v[140:141], off offset:528
	s_mov_b32 s54, 0x30000
	s_mov_b32 s55, 0
	global_load_dwordx4 v[176:179], v[244:245], off offset:2048 nt
	global_load_dwordx4 v[180:183], v[244:245], off offset:2304 nt
	v_lshl_add_u64 v[244:245], v[244:245], 0, s[54:55]
	global_load_dwordx4 v[184:187], v[244:245], off offset:2048 nt
	global_load_dwordx4 v[188:191], v[244:245], off offset:2304 nt
	v_lshl_add_u64 v[244:245], v[244:245], 0, s[54:55]
	global_load_dwordx4 v[192:195], v[244:245], off offset:2048 nt
	global_load_dwordx4 v[196:199], v[244:245], off offset:2304 nt
	v_lshl_add_u64 v[244:245], v[244:245], 0, s[54:55]
	global_load_dwordx4 v[200:203], v[244:245], off offset:2048 nt
	global_load_dwordx4 v[204:207], v[244:245], off offset:2304 nt
	s_mov_b32 s54, 0xf0000
	v_lshl_add_u64 v[244:245], v[244:245], 0, s[54:55]
	s_mov_b32 s54, 0x30000
	global_load_dwordx4 v[208:211], v[244:245], off offset:2048 nt
	global_load_dwordx4 v[212:215], v[244:245], off offset:2304 nt
	v_lshl_add_u64 v[244:245], v[244:245], 0, s[54:55]
	global_load_dwordx4 v[216:219], v[244:245], off offset:2048 nt
	global_load_dwordx4 v[220:223], v[244:245], off offset:2304 nt
	v_lshl_add_u64 v[244:245], v[244:245], 0, s[54:55]
	global_load_dwordx4 v[228:231], v[244:245], off offset:2048 nt
	global_load_dwordx4 v[232:235], v[244:245], off offset:2304 nt
	v_lshl_add_u64 v[244:245], v[244:245], 0, s[54:55]
	global_load_dwordx4 v[236:239], v[244:245], off offset:2048 nt
	global_load_dwordx4 v[240:243], v[244:245], off offset:2304 nt
	v_ashrrev_i32_e32 v147, 31, v146
	v_lshlrev_b64 v[172:173], 12, v[146:147]
	v_lshl_add_u64 v[172:173], s[8:9], 0, v[172:173]
	v_lshl_add_u64 v[172:173], v[172:173], 0, v[142:143]
	s_mov_b32 s54, 0x10000
	s_waitcnt vmcnt(15)
	v_mul_f32_e32 v124, v124, v156
	v_mul_f32_e32 v120, v120, v160
	v_mul_f32_e32 v125, v125, v157
	v_mul_f32_e32 v121, v121, v161
	v_mul_f32_e32 v126, v126, v158
	v_mul_f32_e32 v122, v122, v162
	v_mul_f32_e32 v127, v127, v159
	v_mul_f32_e32 v123, v123, v163
	v_lshlrev_b32_e32 v246, 16, v176
	v_and_b32_e32 v247, 0xffff0000, v176
	v_lshlrev_b32_e32 v248, 16, v177
	v_and_b32_e32 v249, 0xffff0000, v177
	v_lshlrev_b32_e32 v250, 16, v178
	v_and_b32_e32 v155, 0xffff0000, v178
	v_lshlrev_b32_e32 v146, 16, v179
	v_and_b32_e32 v147, 0xffff0000, v179
	v_mul_f32_e32 v124, v124, v246
	v_mul_f32_e32 v120, v120, v250
	v_mul_f32_e32 v125, v125, v247
	v_mul_f32_e32 v121, v121, v155
	v_mul_f32_e32 v126, v126, v248
	v_mul_f32_e32 v122, v122, v146
	v_mul_f32_e32 v127, v127, v249
	v_mul_f32_e32 v123, v123, v147
	v_cvt_pk_bf16_f32 v124, v124, v125
	v_cvt_pk_bf16_f32 v125, v126, v127
	v_cvt_pk_bf16_f32 v126, v120, v121
	v_cvt_pk_bf16_f32 v127, v122, v123
	global_store_dwordx4 v[172:173], v[124:127], off
	s_waitcnt vmcnt(15)
	v_mul_f32_e32 v116, v116, v164
	v_mul_f32_e32 v112, v112, v168
	v_mul_f32_e32 v117, v117, v165
	v_mul_f32_e32 v113, v113, v169
	v_mul_f32_e32 v118, v118, v166
	v_mul_f32_e32 v114, v114, v170
	v_mul_f32_e32 v119, v119, v167
	v_mul_f32_e32 v115, v115, v171
	v_lshlrev_b32_e32 v246, 16, v180
	v_and_b32_e32 v247, 0xffff0000, v180
	v_lshlrev_b32_e32 v248, 16, v181
	v_and_b32_e32 v249, 0xffff0000, v181
	v_lshlrev_b32_e32 v250, 16, v182
	v_and_b32_e32 v155, 0xffff0000, v182
	v_lshlrev_b32_e32 v146, 16, v183
	v_and_b32_e32 v147, 0xffff0000, v183
	v_mul_f32_e32 v116, v116, v246
	v_mul_f32_e32 v112, v112, v250
	v_mul_f32_e32 v117, v117, v247
	v_mul_f32_e32 v113, v113, v155
	v_mul_f32_e32 v118, v118, v248
	v_mul_f32_e32 v114, v114, v146
	v_mul_f32_e32 v119, v119, v249
	v_mul_f32_e32 v115, v115, v147
	v_cvt_pk_bf16_f32 v116, v116, v117
	v_cvt_pk_bf16_f32 v117, v118, v119
	v_cvt_pk_bf16_f32 v118, v112, v113
	v_cvt_pk_bf16_f32 v119, v114, v115
	global_store_dwordx4 v[172:173], v[116:119], off offset:256
	v_lshl_add_u64 v[172:173], v[172:173], 0, s[54:55]
	s_waitcnt vmcnt(15)
	v_mul_f32_e32 v108, v108, v156
	v_mul_f32_e32 v104, v104, v160
	v_mul_f32_e32 v109, v109, v157
	v_mul_f32_e32 v105, v105, v161
	v_mul_f32_e32 v110, v110, v158
	v_mul_f32_e32 v106, v106, v162
	v_mul_f32_e32 v111, v111, v159
	v_mul_f32_e32 v107, v107, v163
	v_lshlrev_b32_e32 v246, 16, v184
	v_and_b32_e32 v247, 0xffff0000, v184
	v_lshlrev_b32_e32 v248, 16, v185
	v_and_b32_e32 v249, 0xffff0000, v185
	v_lshlrev_b32_e32 v250, 16, v186
	v_and_b32_e32 v155, 0xffff0000, v186
	v_lshlrev_b32_e32 v146, 16, v187
	v_and_b32_e32 v147, 0xffff0000, v187
	v_mul_f32_e32 v108, v108, v246
	v_mul_f32_e32 v104, v104, v250
	v_mul_f32_e32 v109, v109, v247
	v_mul_f32_e32 v105, v105, v155
	v_mul_f32_e32 v110, v110, v248
	v_mul_f32_e32 v106, v106, v146
	v_mul_f32_e32 v111, v111, v249
	v_mul_f32_e32 v107, v107, v147
	v_cvt_pk_bf16_f32 v108, v108, v109
	v_cvt_pk_bf16_f32 v109, v110, v111
	v_cvt_pk_bf16_f32 v110, v104, v105
	v_cvt_pk_bf16_f32 v111, v106, v107
	global_store_dwordx4 v[172:173], v[108:111], off
	s_waitcnt vmcnt(15)
; DI void unpack8(const u32x4 w, float (&f)[8]) { f[0] = bflo(w.x); f[1] = bfhi(w.x); f[2] = bflo(w.y); f[3] = bfhi(w.y); f[4] = bflo(w.z); f[5] = bfhi(w.z); f[6] = bflo(w.w); f[7] = bfhi(w.w); }
; DI u32x4 pack8(const float (&f)[8]) { u32x4 w; w.x = pk2(f[0], f[1]); w.y = pk2(f[2], f[3]); w.z = pk2(f[4], f[5]); w.w = pk2(f[6], f[7]); return w; }
;     DI void operator()(const f32x4 (&acc)[2][2][4][2], const pg8::Unit& u, int wr, int wc, int fr, int fq) const {
;     ...
;         for (int ai = 0; ai < 2; ++ai)
; #pragma unroll
;             for (int m = 0; m < 4; ++m) { const size_t row = row0 + ai * 128 + m * 16;
; #pragma unroll
;                 for (int bj = 0; bj < 2; ++bj) { const int col = colt + bj * 128; const f32x4 v0 = acc[ai][bj][m][0], v1 = acc[ai][bj][m][1];
;                     float gc[8]; unpack8(__builtin_nontemporal_load((const u32x4*)(Z1 + row * NIN_O + 1024 + col)), gc);
;                     const f32x4 s0 = *(const f32x4*)(ps + col), s1 = *(const f32x4*)(ps + col + 4);
;                     float y[8];
; #pragma unroll
;                     for (int k = 0; k < 4; ++k) { y[k] = v0[k] * s0[k] * gc[k]; y[4 + k] = v1[k] * s1[k] * gc[4 + k]; }
;                     *(u32x4*)(Y + row * 2048 + col) = pack8(y); }
;                 asm volatile("" ::: "memory"); }
	v_mul_f32_e32 v100, v100, v164
	v_mul_f32_e32 v96, v96, v168
	v_mul_f32_e32 v101, v101, v165
	v_mul_f32_e32 v97, v97, v169
	v_mul_f32_e32 v102, v102, v166
	v_mul_f32_e32 v98, v98, v170
	v_mul_f32_e32 v103, v103, v167
	v_mul_f32_e32 v99, v99, v171
	v_lshlrev_b32_e32 v246, 16, v188
	v_and_b32_e32 v247, 0xffff0000, v188
	v_lshlrev_b32_e32 v248, 16, v189
	v_and_b32_e32 v249, 0xffff0000, v189
	v_lshlrev_b32_e32 v250, 16, v190
	v_and_b32_e32 v155, 0xffff0000, v190
	v_lshlrev_b32_e32 v146, 16, v191
	v_and_b32_e32 v147, 0xffff0000, v191
	v_mul_f32_e32 v100, v100, v246
	v_mul_f32_e32 v96, v96, v250
	v_mul_f32_e32 v101, v101, v247
	v_mul_f32_e32 v97, v97, v155
	v_mul_f32_e32 v102, v102, v248
	v_mul_f32_e32 v98, v98, v146
	v_mul_f32_e32 v103, v103, v249
	v_mul_f32_e32 v99, v99, v147
	v_cvt_pk_bf16_f32 v100, v100, v101
	v_cvt_pk_bf16_f32 v101, v102, v103
	v_cvt_pk_bf16_f32 v102, v96, v97
	v_cvt_pk_bf16_f32 v103, v98, v99
	global_store_dwordx4 v[172:173], v[100:103], off offset:256
	v_lshl_add_u64 v[172:173], v[172:173], 0, s[54:55]
	s_waitcnt vmcnt(15)
	v_mul_f32_e32 v92, v92, v156
	v_mul_f32_e32 v88, v88, v160
	v_mul_f32_e32 v93, v93, v157
	v_mul_f32_e32 v89, v89, v161
	v_mul_f32_e32 v94, v94, v158
	v_mul_f32_e32 v90, v90, v162
	v_mul_f32_e32 v95, v95, v159
	v_mul_f32_e32 v91, v91, v163
	v_lshlrev_b32_e32 v246, 16, v192
	v_and_b32_e32 v247, 0xffff0000, v192
	v_lshlrev_b32_e32 v248, 16, v193
	v_and_b32_e32 v249, 0xffff0000, v193
	v_lshlrev_b32_e32 v250, 16, v194
	v_and_b32_e32 v155, 0xffff0000, v194
	v_lshlrev_b32_e32 v146, 16, v195
	v_and_b32_e32 v147, 0xffff0000, v195
	v_mul_f32_e32 v92, v92, v246
	v_mul_f32_e32 v88, v88, v250
	v_mul_f32_e32 v93, v93, v247
	v_mul_f32_e32 v89, v89, v155
	v_mul_f32_e32 v94, v94, v248
	v_mul_f32_e32 v90, v90, v146
	v_mul_f32_e32 v95, v95, v249
	v_mul_f32_e32 v91, v91, v147
	v_cvt_pk_bf16_f32 v92, v92, v93
	v_cvt_pk_bf16_f32 v93, v94, v95
	v_cvt_pk_bf16_f32 v94, v88, v89
	v_cvt_pk_bf16_f32 v95, v90, v91
	global_store_dwordx4 v[172:173], v[92:95], off
	s_waitcnt vmcnt(15)
	v_mul_f32_e32 v84, v84, v164
	v_mul_f32_e32 v80, v80, v168
	v_mul_f32_e32 v85, v85, v165
	v_mul_f32_e32 v81, v81, v169
	v_mul_f32_e32 v86, v86, v166
	v_mul_f32_e32 v82, v82, v170
	v_mul_f32_e32 v87, v87, v167
	v_mul_f32_e32 v83, v83, v171
	v_lshlrev_b32_e32 v246, 16, v196
	v_and_b32_e32 v247, 0xffff0000, v196
	v_lshlrev_b32_e32 v248, 16, v197
	v_and_b32_e32 v249, 0xffff0000, v197
	v_lshlrev_b32_e32 v250, 16, v198
	v_and_b32_e32 v155, 0xffff0000, v198
	v_lshlrev_b32_e32 v146, 16, v199
	v_and_b32_e32 v147, 0xffff0000, v199
	v_mul_f32_e32 v84, v84, v246
	v_mul_f32_e32 v80, v80, v250
	v_mul_f32_e32 v85, v85, v247
	v_mul_f32_e32 v81, v81, v155
	v_mul_f32_e32 v86, v86, v248
	v_mul_f32_e32 v82, v82, v146
	v_mul_f32_e32 v87, v87, v249
	v_mul_f32_e32 v83, v83, v147
	v_cvt_pk_bf16_f32 v84, v84, v85
	v_cvt_pk_bf16_f32 v85, v86, v87
	v_cvt_pk_bf16_f32 v86, v80, v81
	v_cvt_pk_bf16_f32 v87, v82, v83
	global_store_dwordx4 v[172:173], v[84:87], off offset:256
	v_lshl_add_u64 v[172:173], v[172:173], 0, s[54:55]
	s_waitcnt vmcnt(15)
	v_mul_f32_e32 v76, v76, v156
	v_mul_f32_e32 v72, v72, v160
	v_mul_f32_e32 v77, v77, v157
	v_mul_f32_e32 v73, v73, v161
	v_mul_f32_e32 v78, v78, v158
	v_mul_f32_e32 v74, v74, v162
	v_mul_f32_e32 v79, v79, v159
	v_mul_f32_e32 v75, v75, v163
	v_lshlrev_b32_e32 v246, 16, v200
	v_and_b32_e32 v247, 0xffff0000, v200
	v_lshlrev_b32_e32 v248, 16, v201
	v_and_b32_e32 v249, 0xffff0000, v201
	v_lshlrev_b32_e32 v250, 16, v202
	v_and_b32_e32 v155, 0xffff0000, v202
	v_lshlrev_b32_e32 v146, 16, v203
	v_and_b32_e32 v147, 0xffff0000, v203
	v_mul_f32_e32 v76, v76, v246
	v_mul_f32_e32 v72, v72, v250
	v_mul_f32_e32 v77, v77, v247
	v_mul_f32_e32 v73, v73, v155
	v_mul_f32_e32 v78, v78, v248
	v_mul_f32_e32 v74, v74, v146
	v_mul_f32_e32 v79, v79, v249
	v_mul_f32_e32 v75, v75, v147
	v_cvt_pk_bf16_f32 v76, v76, v77
	v_cvt_pk_bf16_f32 v77, v78, v79
	v_cvt_pk_bf16_f32 v78, v72, v73
	v_cvt_pk_bf16_f32 v79, v74, v75
	global_store_dwordx4 v[172:173], v[76:79], off
	s_waitcnt vmcnt(15)
	v_mul_f32_e32 v68, v68, v164
	v_mul_f32_e32 v64, v64, v168
	v_mul_f32_e32 v69, v69, v165
	v_mul_f32_e32 v65, v65, v169
	v_mul_f32_e32 v70, v70, v166
	v_mul_f32_e32 v66, v66, v170
	v_mul_f32_e32 v71, v71, v167
	v_mul_f32_e32 v67, v67, v171
	v_lshlrev_b32_e32 v246, 16, v204
	v_and_b32_e32 v247, 0xffff0000, v204
	v_lshlrev_b32_e32 v248, 16, v205
	v_and_b32_e32 v249, 0xffff0000, v205
	v_lshlrev_b32_e32 v250, 16, v206
	v_and_b32_e32 v155, 0xffff0000, v206
	v_lshlrev_b32_e32 v146, 16, v207
	v_and_b32_e32 v147, 0xffff0000, v207
	v_mul_f32_e32 v68, v68, v246
	v_mul_f32_e32 v64, v64, v250
	v_mul_f32_e32 v69, v69, v247
	v_mul_f32_e32 v65, v65, v155
	v_mul_f32_e32 v70, v70, v248
	v_mul_f32_e32 v66, v66, v146
	v_mul_f32_e32 v71, v71, v249
	v_mul_f32_e32 v67, v67, v147
	v_cvt_pk_bf16_f32 v68, v68, v69
	v_cvt_pk_bf16_f32 v69, v70, v71
	v_cvt_pk_bf16_f32 v70, v64, v65
	v_cvt_pk_bf16_f32 v71, v66, v67
	global_store_dwordx4 v[172:173], v[68:71], off offset:256
	s_mov_b32 s54, 0x50000
	v_lshl_add_u64 v[172:173], v[172:173], 0, s[54:55]
	s_mov_b32 s54, 0x10000
	s_waitcnt vmcnt(15)
	v_mul_f32_e32 v60, v60, v156
	v_mul_f32_e32 v56, v56, v160
	v_mul_f32_e32 v61, v61, v157
	v_mul_f32_e32 v57, v57, v161
	v_mul_f32_e32 v62, v62, v158
	v_mul_f32_e32 v58, v58, v162
	v_mul_f32_e32 v63, v63, v159
	v_mul_f32_e32 v59, v59, v163
	v_lshlrev_b32_e32 v246, 16, v208
	v_and_b32_e32 v247, 0xffff0000, v208
	v_lshlrev_b32_e32 v248, 16, v209
	v_and_b32_e32 v249, 0xffff0000, v209
	v_lshlrev_b32_e32 v250, 16, v210
	v_and_b32_e32 v155, 0xffff0000, v210
	v_lshlrev_b32_e32 v146, 16, v211
	v_and_b32_e32 v147, 0xffff0000, v211
	v_mul_f32_e32 v60, v60, v246
	v_mul_f32_e32 v56, v56, v250
	v_mul_f32_e32 v61, v61, v247
	v_mul_f32_e32 v57, v57, v155
	v_mul_f32_e32 v62, v62, v248
	v_mul_f32_e32 v58, v58, v146
	v_mul_f32_e32 v63, v63, v249
	v_mul_f32_e32 v59, v59, v147
	v_cvt_pk_bf16_f32 v60, v60, v61
	v_cvt_pk_bf16_f32 v61, v62, v63
	v_cvt_pk_bf16_f32 v62, v56, v57
	v_cvt_pk_bf16_f32 v63, v58, v59
	global_store_dwordx4 v[172:173], v[60:63], off
	s_waitcnt vmcnt(15)
; DI void unpack8(const u32x4 w, float (&f)[8]) { f[0] = bflo(w.x); f[1] = bfhi(w.x); f[2] = bflo(w.y); f[3] = bfhi(w.y); f[4] = bflo(w.z); f[5] = bfhi(w.z); f[6] = bflo(w.w); f[7] = bfhi(w.w); }
; DI u32x4 pack8(const float (&f)[8]) { u32x4 w; w.x = pk2(f[0], f[1]); w.y = pk2(f[2], f[3]); w.z = pk2(f[4], f[5]); w.w = pk2(f[6], f[7]); return w; }
;     DI void operator()(const f32x4 (&acc)[2][2][4][2], const pg8::Unit& u, int wr, int wc, int fr, int fq) const {
;     ...
;         for (int ai = 0; ai < 2; ++ai)
; #pragma unroll
;             for (int m = 0; m < 4; ++m) { const size_t row = row0 + ai * 128 + m * 16;
; #pragma unroll
;                 for (int bj = 0; bj < 2; ++bj) { const int col = colt + bj * 128; const f32x4 v0 = acc[ai][bj][m][0], v1 = acc[ai][bj][m][1];
;                     float gc[8]; unpack8(__builtin_nontemporal_load((const u32x4*)(Z1 + row * NIN_O + 1024 + col)), gc);
;                     const f32x4 s0 = *(const f32x4*)(ps + col), s1 = *(const f32x4*)(ps + col + 4);
;                     float y[8];
; #pragma unroll
;                     for (int k = 0; k < 4; ++k) { y[k] = v0[k] * s0[k] * gc[k]; y[4 + k] = v1[k] * s1[k] * gc[4 + k]; }
;                     *(u32x4*)(Y + row * 2048 + col) = pack8(y); }
;                 asm volatile("" ::: "memory"); }
;     }
	v_mul_f32_e32 v52, v52, v164
	v_mul_f32_e32 v48, v48, v168
	v_mul_f32_e32 v53, v53, v165
	v_mul_f32_e32 v49, v49, v169
	v_mul_f32_e32 v54, v54, v166
	v_mul_f32_e32 v50, v50, v170
	v_mul_f32_e32 v55, v55, v167
	v_mul_f32_e32 v51, v51, v171
	v_lshlrev_b32_e32 v246, 16, v212
	v_and_b32_e32 v247, 0xffff0000, v212
	v_lshlrev_b32_e32 v248, 16, v213
	v_and_b32_e32 v249, 0xffff0000, v213
	v_lshlrev_b32_e32 v250, 16, v214
	v_and_b32_e32 v155, 0xffff0000, v214
	v_lshlrev_b32_e32 v146, 16, v215
	v_and_b32_e32 v147, 0xffff0000, v215
	v_mul_f32_e32 v52, v52, v246
	v_mul_f32_e32 v48, v48, v250
	v_mul_f32_e32 v53, v53, v247
	v_mul_f32_e32 v49, v49, v155
	v_mul_f32_e32 v54, v54, v248
	v_mul_f32_e32 v50, v50, v146
	v_mul_f32_e32 v55, v55, v249
	v_mul_f32_e32 v51, v51, v147
	v_cvt_pk_bf16_f32 v52, v52, v53
	v_cvt_pk_bf16_f32 v53, v54, v55
	v_cvt_pk_bf16_f32 v54, v48, v49
	v_cvt_pk_bf16_f32 v55, v50, v51
	global_store_dwordx4 v[172:173], v[52:55], off offset:256
	v_lshl_add_u64 v[172:173], v[172:173], 0, s[54:55]
	s_waitcnt vmcnt(15)
	v_mul_f32_e32 v44, v44, v156
	v_mul_f32_e32 v40, v40, v160
	v_mul_f32_e32 v45, v45, v157
	v_mul_f32_e32 v41, v41, v161
	v_mul_f32_e32 v46, v46, v158
	v_mul_f32_e32 v42, v42, v162
	v_mul_f32_e32 v47, v47, v159
	v_mul_f32_e32 v43, v43, v163
	v_lshlrev_b32_e32 v246, 16, v216
	v_and_b32_e32 v247, 0xffff0000, v216
	v_lshlrev_b32_e32 v248, 16, v217
	v_and_b32_e32 v249, 0xffff0000, v217
	v_lshlrev_b32_e32 v250, 16, v218
	v_and_b32_e32 v155, 0xffff0000, v218
	v_lshlrev_b32_e32 v146, 16, v219
	v_and_b32_e32 v147, 0xffff0000, v219
	v_mul_f32_e32 v44, v44, v246
	v_mul_f32_e32 v40, v40, v250
	v_mul_f32_e32 v45, v45, v247
	v_mul_f32_e32 v41, v41, v155
	v_mul_f32_e32 v46, v46, v248
	v_mul_f32_e32 v42, v42, v146
	v_mul_f32_e32 v47, v47, v249
	v_mul_f32_e32 v43, v43, v147
	v_cvt_pk_bf16_f32 v44, v44, v45
	v_cvt_pk_bf16_f32 v45, v46, v47
	v_cvt_pk_bf16_f32 v46, v40, v41
	v_cvt_pk_bf16_f32 v47, v42, v43
	global_store_dwordx4 v[172:173], v[44:47], off
	s_waitcnt vmcnt(15)
	v_mul_f32_e32 v36, v36, v164
	v_mul_f32_e32 v32, v32, v168
	v_mul_f32_e32 v37, v37, v165
	v_mul_f32_e32 v33, v33, v169
	v_mul_f32_e32 v38, v38, v166
	v_mul_f32_e32 v34, v34, v170
	v_mul_f32_e32 v39, v39, v167
	v_mul_f32_e32 v35, v35, v171
	v_lshlrev_b32_e32 v246, 16, v220
	v_and_b32_e32 v247, 0xffff0000, v220
	v_lshlrev_b32_e32 v248, 16, v221
	v_and_b32_e32 v249, 0xffff0000, v221
	v_lshlrev_b32_e32 v250, 16, v222
	v_and_b32_e32 v155, 0xffff0000, v222
	v_lshlrev_b32_e32 v146, 16, v223
	v_and_b32_e32 v147, 0xffff0000, v223
	v_mul_f32_e32 v36, v36, v246
	v_mul_f32_e32 v32, v32, v250
	v_mul_f32_e32 v37, v37, v247
	v_mul_f32_e32 v33, v33, v155
	v_mul_f32_e32 v38, v38, v248
	v_mul_f32_e32 v34, v34, v146
	v_mul_f32_e32 v39, v39, v249
	v_mul_f32_e32 v35, v35, v147
	v_cvt_pk_bf16_f32 v36, v36, v37
	v_cvt_pk_bf16_f32 v37, v38, v39
	v_cvt_pk_bf16_f32 v38, v32, v33
	v_cvt_pk_bf16_f32 v39, v34, v35
	global_store_dwordx4 v[172:173], v[36:39], off offset:256
	v_lshl_add_u64 v[172:173], v[172:173], 0, s[54:55]
	s_waitcnt vmcnt(15)
	v_mul_f32_e32 v28, v28, v156
	v_mul_f32_e32 v24, v24, v160
	v_mul_f32_e32 v29, v29, v157
	v_mul_f32_e32 v25, v25, v161
	v_mul_f32_e32 v30, v30, v158
	v_mul_f32_e32 v26, v26, v162
	v_mul_f32_e32 v31, v31, v159
	v_mul_f32_e32 v27, v27, v163
	v_lshlrev_b32_e32 v246, 16, v228
	v_and_b32_e32 v247, 0xffff0000, v228
	v_lshlrev_b32_e32 v248, 16, v229
	v_and_b32_e32 v249, 0xffff0000, v229
	v_lshlrev_b32_e32 v250, 16, v230
	v_and_b32_e32 v155, 0xffff0000, v230
	v_lshlrev_b32_e32 v146, 16, v231
	v_and_b32_e32 v147, 0xffff0000, v231
	v_mul_f32_e32 v28, v28, v246
	v_mul_f32_e32 v24, v24, v250
	v_mul_f32_e32 v29, v29, v247
	v_mul_f32_e32 v25, v25, v155
	v_mul_f32_e32 v30, v30, v248
	v_mul_f32_e32 v26, v26, v146
	v_mul_f32_e32 v31, v31, v249
	v_mul_f32_e32 v27, v27, v147
	v_cvt_pk_bf16_f32 v28, v28, v29
	v_cvt_pk_bf16_f32 v29, v30, v31
	v_cvt_pk_bf16_f32 v30, v24, v25
	v_cvt_pk_bf16_f32 v31, v26, v27
	global_store_dwordx4 v[172:173], v[28:31], off
	s_waitcnt vmcnt(15)
	v_mul_f32_e32 v20, v20, v164
	v_mul_f32_e32 v16, v16, v168
	v_mul_f32_e32 v21, v21, v165
	v_mul_f32_e32 v17, v17, v169
	v_mul_f32_e32 v22, v22, v166
	v_mul_f32_e32 v18, v18, v170
	v_mul_f32_e32 v23, v23, v167
	v_mul_f32_e32 v19, v19, v171
	v_lshlrev_b32_e32 v246, 16, v232
	v_and_b32_e32 v247, 0xffff0000, v232
	v_lshlrev_b32_e32 v248, 16, v233
	v_and_b32_e32 v249, 0xffff0000, v233
	v_lshlrev_b32_e32 v250, 16, v234
	v_and_b32_e32 v155, 0xffff0000, v234
	v_lshlrev_b32_e32 v146, 16, v235
	v_and_b32_e32 v147, 0xffff0000, v235
	v_mul_f32_e32 v20, v20, v246
	v_mul_f32_e32 v16, v16, v250
	v_mul_f32_e32 v21, v21, v247
	v_mul_f32_e32 v17, v17, v155
	v_mul_f32_e32 v22, v22, v248
	v_mul_f32_e32 v18, v18, v146
	v_mul_f32_e32 v23, v23, v249
	v_mul_f32_e32 v19, v19, v147
	v_cvt_pk_bf16_f32 v20, v20, v21
	v_cvt_pk_bf16_f32 v21, v22, v23
	v_cvt_pk_bf16_f32 v22, v16, v17
	v_cvt_pk_bf16_f32 v23, v18, v19
	global_store_dwordx4 v[172:173], v[20:23], off offset:256
	v_lshl_add_u64 v[172:173], v[172:173], 0, s[54:55]
	s_waitcnt vmcnt(15)
	v_mul_f32_e32 v12, v12, v156
	v_mul_f32_e32 v8, v8, v160
	v_mul_f32_e32 v13, v13, v157
	v_mul_f32_e32 v9, v9, v161
	v_mul_f32_e32 v14, v14, v158
	v_mul_f32_e32 v10, v10, v162
	v_mul_f32_e32 v15, v15, v159
	v_mul_f32_e32 v11, v11, v163
	v_lshlrev_b32_e32 v246, 16, v236
	v_and_b32_e32 v247, 0xffff0000, v236
	v_lshlrev_b32_e32 v248, 16, v237
	v_and_b32_e32 v249, 0xffff0000, v237
	v_lshlrev_b32_e32 v250, 16, v238
	v_and_b32_e32 v155, 0xffff0000, v238
	v_lshlrev_b32_e32 v146, 16, v239
	v_and_b32_e32 v147, 0xffff0000, v239
	v_mul_f32_e32 v12, v12, v246
	v_mul_f32_e32 v8, v8, v250
	v_mul_f32_e32 v13, v13, v247
	v_mul_f32_e32 v9, v9, v155
	v_mul_f32_e32 v14, v14, v248
	v_mul_f32_e32 v10, v10, v146
	v_mul_f32_e32 v15, v15, v249
	v_mul_f32_e32 v11, v11, v147
	v_cvt_pk_bf16_f32 v12, v12, v13
	v_cvt_pk_bf16_f32 v13, v14, v15
	v_cvt_pk_bf16_f32 v14, v8, v9
	v_cvt_pk_bf16_f32 v15, v10, v11
	global_store_dwordx4 v[172:173], v[12:15], off
	s_waitcnt vmcnt(15)
	v_mul_f32_e32 v4, v4, v164
	v_mul_f32_e32 v0, v0, v168
	v_mul_f32_e32 v5, v5, v165
	v_mul_f32_e32 v1, v1, v169
	v_mul_f32_e32 v6, v6, v166
	v_mul_f32_e32 v2, v2, v170
	v_mul_f32_e32 v7, v7, v167
	v_mul_f32_e32 v3, v3, v171
	v_lshlrev_b32_e32 v246, 16, v240
	v_and_b32_e32 v247, 0xffff0000, v240
	v_lshlrev_b32_e32 v248, 16, v241
	v_and_b32_e32 v249, 0xffff0000, v241
	v_lshlrev_b32_e32 v250, 16, v242
	v_and_b32_e32 v155, 0xffff0000, v242
	v_lshlrev_b32_e32 v146, 16, v243
	v_and_b32_e32 v147, 0xffff0000, v243
	v_mul_f32_e32 v4, v4, v246
	v_mul_f32_e32 v0, v0, v250
	v_mul_f32_e32 v5, v5, v247
	v_mul_f32_e32 v1, v1, v155
	v_mul_f32_e32 v6, v6, v248
	v_mul_f32_e32 v2, v2, v146
	v_mul_f32_e32 v7, v7, v249
	v_mul_f32_e32 v3, v3, v147
	v_cvt_pk_bf16_f32 v4, v4, v5
	v_cvt_pk_bf16_f32 v5, v6, v7
	v_cvt_pk_bf16_f32 v6, v0, v1
	v_cvt_pk_bf16_f32 v7, v2, v3
	global_store_dwordx4 v[172:173], v[4:7], off offset:256
	s_andn2_b64 vcc, exec, s[6:7]
	s_mov_b64 s[6:7], -1
	s_cbranch_vccnz .LBB0_1897
; #define PG8_BAR __builtin_amdgcn_s_barrier()
; template <class Epi, class Sched, bool ALIGN_EPI = true, bool SP2 = true>
; DI void gemm_phase(LAS unsigned char* lds, const Gemm g, const Sched& S, const Epi& E) {
;     ...
;         if (!has_next) break;
; #pragma unroll
;         for (int a = 0; a < 2; ++a)
; #pragma unroll
;             for (int b = 0; b < 2; ++b)
; #pragma unroll
;                 for (int m = 0; m < 4; ++m)
; #pragma unroll
;                     for (int n = 0; n < 2; ++n) acc[a][b][m][n] = (f32x4){0.f, 0.f, 0.f, 0.f};
;         cur = nxt; cA = nA; cB = nB; ++ui;
;         if constexpr (ALIGN_EPI) { if (wr == 1) PG8_BAR; }
;     }
	s_andn2_b64 vcc, exec, s[14:15]
	s_cbranch_vccnz .LBB0_1896
	s_barrier
	s_branch .LBB0_1896
